# asel: per-step count via one wave-wide load per 64 steps + v_readlane (removes a dependent load per loop step)
# baseline (speedup 1.0000x reference)
.LBB0_1243:
	s_or_b64 exec, exec, s[0:1]
	s_add_u32 s46, s56, 0x10000000
	s_addc_u32 s47, s57, 0
	v_mov_b32_e32 v0, v196
	s_cmpk_gt_i32 s12, 0x3dff
	s_waitcnt lgkmcnt(0)
	s_barrier
	s_cbranch_scc1 .LBB0_1384
	v_bfe_u32 v1, v0, 5, 1
	v_ashrrev_i32_e32 v2, 1, v0
	s_movk_i32 s0, 0xffe0
	s_waitcnt vmcnt(0)
	v_lshlrev_b32_e32 v100, 4, v1
	v_mov_b32_e32 v101, 0
	s_add_u32 s52, s56, 0x2e00000
	v_and_b32_e32 v105, 31, v0
	v_and_b32_e32 v106, 0xffffffe0, v2
	v_bfi_b32 v107, s0, v2, v0
	v_lshl_add_u64 v[102:103], s[6:7], 0, v[100:101]
	s_addc_u32 s53, s57, 0
	v_lshlrev_b32_e32 v104, 2, v1
	v_cmp_eq_u32_e64 s[2:3], 0, v1
	s_movk_i32 s60, 0x208
	s_mov_b32 s61, 0x8000
	s_mov_b32 s62, 0x20000
	s_mov_b32 s63, 0x40000
	s_mov_b32 s64, 0x60000
	s_mov_b32 s65, 0x80000
	s_mov_b32 s66, 0xa0000
	s_mov_b32 s67, 0xc0000
	s_mov_b32 s68, 0xe0000
	s_movk_i32 s69, 0x1fff
	s_mov_b32 s70, 0xf149f2ca
	v_mbcnt_hi_u32_b32 v108, -1, v253
	v_mov_b32_e32 v109, 13
	s_mov_b32 s71, s12
	s_mov_b32 s76, 0
	s_branch .LBB0_1247

.LBB0_1246:
	s_add_i32 s71, s71, s58
	s_add_i32 s76, s76, 1
	s_cmpk_lt_i32 s71, 0x3e00
	s_cbranch_scc0 .LBB0_1384
.LBB0_1247:
	s_and_b32 s77, s76, 63
	s_cmp_lg_u32 s77, 0
	s_cbranch_scc1 .Lasc_have
	v_mbcnt_lo_u32_b32 v0, -1, 0
	v_mbcnt_hi_u32_b32 v0, -1, v0
	v_mul_lo_u32 v0, v0, s58
	v_add_u32_e32 v0, s71, v0
	v_min_u32_e32 v0, 0x3dff, v0
	v_lshrrev_b32_e32 v1, 6, v0
	v_mul_u32_u24_e32 v1, 0x843, v1
	v_lshrrev_b32_e32 v1, 16, v1
	v_mul_u32_u24_e32 v2, 0x7c0, v1
	v_sub_u32_e32 v0, v0, v2
	v_and_b32_e32 v1, 7, v0
	v_mul_u32_u24_e32 v1, 0xf8, v1
	v_bfe_u32 v2, v0, 3, 3
	v_mul_u32_u24_e32 v2, 31, v2
	v_lshrrev_b32_e32 v3, 6, v0
	v_add3_u32 v0, v1, v2, v3
	v_lshlrev_b32_e32 v0, 2, v0
	global_load_dword v250, v0, s[16:17]
	s_waitcnt vmcnt(0)
.Lasc_have:
	s_mul_hi_i32 s0, s71, 0x84210843
	s_add_i32 s0, s0, s71
	s_lshr_b32 s1, s0, 31
	s_ashr_i32 s0, s0, 10
	s_add_i32 s1, s0, s1
	s_mul_i32 s0, s1, 0xfffff840
	s_add_i32 s34, s0, s71
	s_and_b32 s0, s34, 7
	s_mulk_i32 s0, 0xf8
	s_bfe_u32 s4, s34, 0x30003
	s_mulk_i32 s4, 31
	s_add_i32 s0, s0, s4
	s_lshr_b32 s4, s34, 6
	s_add_i32 s34, s0, s4
	s_mul_hi_i32 s0, s34, 0x84210843
	s_add_i32 s0, s0, s34
	s_lshr_b32 s4, s0, 31
	s_ashr_i32 s0, s0, 4
	s_add_i32 s0, s0, s4
	s_mul_i32 s14, s0, 0xffffffe1
	s_add_i32 s14, s14, s34
	s_lshl_b32 s4, s14, 8
	s_lshl_b32 s15, s1, 10
	s_sub_i32 s5, 0x1f00, s4
	s_cmp_ge_i32 s15, s5
	s_cbranch_scc1 .LBB0_1246
	s_ashr_i32 s35, s34, 31
	s_lshl_b32 s11, s1, 3
	s_lshl_b64 s[34:35], s[34:35], 2
	s_add_u32 s34, s16, s34
	s_addc_u32 s35, s17, s35
	s_waitcnt vmcnt(0)
	v_readlane_b32 s1, v250, s77
	s_nop 1
	v_mov_b32_e32 v110, s1
	s_addk_i32 s1, 0x7f
	s_ashr_i32 s10, s1, 7
	s_cmp_ge_i32 s11, s10
	s_cbranch_scc1 .LBB0_1246
	s_ashr_i32 s1, s0, 31
	s_lshl_b64 s[38:39], s[0:1], 13
	s_ashr_i32 s5, s4, 31
	s_add_u32 s34, s38, s4
	s_addc_u32 s35, s39, s5
	s_lshl_b64 s[34:35], s[34:35], 7
	s_add_u32 s34, s26, s34
	s_addc_u32 s35, s27, s35
	s_lshl_b64 s[36:37], s[0:1], 20
	v_mov_b32_e32 v82, v196
	s_barrier
	s_add_u32 s33, s46, s36
	s_addc_u32 s36, s47, s37
	v_ashrrev_i32_e32 v64, 3, v82
	s_lshl_b64 s[4:5], s[4:5], 1
	v_lshlrev_b32_e32 v32, 4, v82
	v_add_u32_e32 v66, 32, v64
	s_add_u32 s4, s33, s4
	v_and_b32_e32 v100, 0x70, v32
	v_ashrrev_i32_e32 v65, 31, v64
	v_ashrrev_i32_e32 v67, 31, v66
	v_ashrrev_i32_e32 v80, 5, v82
	s_addc_u32 s5, s36, s5
	v_lshl_add_u64 v[24:25], s[34:35], 0, v[100:101]
	v_lshlrev_b64 v[0:1], 7, v[64:65]
	v_lshlrev_b64 v[2:3], 7, v[66:67]
	v_add_u32_e32 v68, 64, v64
	v_add_u32_e32 v70, 0x60, v64
	v_and_b32_e32 v100, 0x1f0, v32
	v_ashrrev_i32_e32 v81, 31, v80
	v_lshl_add_u64 v[0:1], v[24:25], 0, v[0:1]
	v_lshl_add_u64 v[4:5], v[24:25], 0, v[2:3]
	v_ashrrev_i32_e32 v69, 31, v68
	v_ashrrev_i32_e32 v71, 31, v70
	v_lshl_add_u64 v[32:33], s[4:5], 0, v[100:101]
	s_waitcnt lgkmcnt(0)
	v_lshlrev_b64 v[34:35], 14, v[80:81]
	global_load_dwordx4 v[0:3], v[0:1], off
	s_nop 0
	global_load_dwordx4 v[4:7], v[4:5], off
	v_lshlrev_b64 v[8:9], 7, v[68:69]
	v_lshlrev_b64 v[10:11], 7, v[70:71]
	v_add_u32_e32 v72, 0x80, v64
	v_add_u32_e32 v74, 0xa0, v64
	v_lshl_add_u64 v[60:61], v[32:33], 0, v[34:35]
	v_lshl_add_u64 v[8:9], v[24:25], 0, v[8:9]
	v_lshl_add_u64 v[12:13], v[24:25], 0, v[10:11]
	v_ashrrev_i32_e32 v73, 31, v72
	v_ashrrev_i32_e32 v75, 31, v74
	v_add_co_u32_e32 v36, vcc, s62, v60
	global_load_dwordx4 v[8:11], v[8:9], off
	s_nop 0
	global_load_dwordx4 v[12:15], v[12:13], off
	v_lshlrev_b64 v[16:17], 7, v[72:73]
	v_lshlrev_b64 v[18:19], 7, v[74:75]
	v_add_u32_e32 v76, 0xc0, v64
	v_add_u32_e32 v78, 0xe0, v64
	v_addc_co_u32_e32 v37, vcc, 0, v61, vcc
	v_lshl_add_u64 v[16:17], v[24:25], 0, v[16:17]
	v_lshl_add_u64 v[20:21], v[24:25], 0, v[18:19]
	v_ashrrev_i32_e32 v77, 31, v76
	v_ashrrev_i32_e32 v79, 31, v78
	v_add_co_u32_e32 v40, vcc, s63, v60
	global_load_dwordx4 v[16:19], v[16:17], off
	s_nop 0
	global_load_dwordx4 v[20:23], v[20:21], off
	v_lshlrev_b64 v[26:27], 7, v[76:77]
	v_lshlrev_b64 v[28:29], 7, v[78:79]
	v_addc_co_u32_e32 v41, vcc, 0, v61, vcc
	v_lshl_add_u64 v[26:27], v[24:25], 0, v[26:27]
	v_lshl_add_u64 v[28:29], v[24:25], 0, v[28:29]
	v_add_co_u32_e32 v44, vcc, s64, v60
	global_load_dwordx4 v[24:27], v[26:27], off
	s_nop 0
	global_load_dwordx4 v[28:31], v[28:29], off
	v_addc_co_u32_e32 v45, vcc, 0, v61, vcc
	v_add_co_u32_e32 v48, vcc, s65, v60
	global_load_dwordx4 v[32:35], v[60:61], off
	s_nop 0
	global_load_dwordx4 v[36:39], v[36:37], off
	v_addc_co_u32_e32 v49, vcc, 0, v61, vcc
	v_add_co_u32_e32 v52, vcc, s66, v60
	global_load_dwordx4 v[40:43], v[40:41], off
	s_nop 0
	global_load_dwordx4 v[44:47], v[44:45], off
	v_addc_co_u32_e32 v53, vcc, 0, v61, vcc
	v_add_co_u32_e32 v56, vcc, s67, v60
	global_load_dwordx4 v[48:51], v[48:49], off
	s_nop 0
	global_load_dwordx4 v[52:55], v[52:53], off
	v_addc_co_u32_e32 v57, vcc, 0, v61, vcc
	v_add_co_u32_e32 v60, vcc, s68, v60
	global_load_dwordx4 v[56:59], v[56:57], off
	s_nop 0
	v_addc_co_u32_e32 v61, vcc, 0, v61, vcc
	global_load_dwordx4 v[60:63], v[60:61], off
	v_lshrrev_b32_e32 v65, 1, v64
	v_xor_b32_e32 v65, v65, v82
	v_lshlrev_b32_e32 v65, 4, v65
	v_and_b32_e32 v65, 0x70, v65
	v_add_u32_e32 v65, 16, v65
	v_lshl_add_u32 v64, v64, 7, v65
	s_add_i32 s33, s11, 8
	s_mul_i32 s5, s0, 0x3e000
	s_mul_hi_i32 s4, s0, 0x3e000
	s_add_u32 s34, s28, s5
	s_addc_u32 s35, s29, s4
	s_not_b32 s4, s14
	s_lshl_b32 s4, s4, 7
	s_addk_i32 s4, 0x2000
	s_mul_i32 s4, s4, s14
	s_ashr_i32 s5, s4, 31
	s_lshl_b64 s[4:5], s[4:5], 1
	s_add_u32 s4, s34, s4
	s_addc_u32 s5, s35, s5
	s_or_b32 s34, s11, 1
	s_lshl_b32 s14, s34, 7
	s_waitcnt vmcnt(15)
	ds_write_b128 v64, v[0:3]
	v_lshl_add_u32 v0, v66, 7, v65
	s_waitcnt vmcnt(14)
	ds_write_b128 v0, v[4:7]
	v_lshl_add_u32 v0, v68, 7, v65
	s_min_i32 s10, s33, s10
	s_cmp_ge_i32 s34, s10
	s_cselect_b64 s[40:41], -1, 0
	s_and_b64 vcc, exec, s[40:41]
	s_waitcnt vmcnt(13)
	ds_write_b128 v0, v[8:11]
	v_lshl_add_u32 v0, v70, 7, v65
	s_waitcnt vmcnt(12)
	ds_write_b128 v0, v[12:15]
	v_lshl_add_u32 v0, v72, 7, v65
	v_add_u32_e32 v12, -1, v110
	v_add_u32_e32 v13, s15, v107
	v_add_u32_e32 v2, 0x100, v13
	v_add_u32_e32 v4, 0x180, v13
	v_add_u32_e32 v6, 0x200, v13
	v_add_u32_e32 v8, 0x280, v13
	v_add_u32_e32 v10, 0x300, v13
	v_min_i32_e32 v2, v2, v12
	v_min_i32_e32 v4, v4, v12
	s_waitcnt vmcnt(11)
	ds_write_b128 v0, v[16:19]
	v_lshl_add_u32 v0, v74, 7, v65
	s_waitcnt vmcnt(10)
	ds_write_b128 v0, v[20:23]
	v_lshl_add_u32 v0, v76, 7, v65
	v_min_i32_e32 v6, v6, v12
	v_min_i32_e32 v8, v8, v12
	v_min_i32_e32 v10, v10, v12
	v_ashrrev_i32_e32 v3, 31, v2
	v_ashrrev_i32_e32 v5, 31, v4
	s_waitcnt vmcnt(9)
	ds_write_b128 v0, v[24:27]
	v_lshl_add_u32 v0, v78, 7, v65
	s_waitcnt vmcnt(8)
	ds_write_b128 v0, v[28:31]
	v_mul_lo_u32 v0, v80, s60
	v_add3_u32 v0, 16, v100, v0
	v_add_u32_e32 v1, 0x8000, v0
	s_waitcnt vmcnt(7)
	ds_write2_b64 v1, v[32:33], v[34:35] offset1:1
	v_add_u32_e32 v1, 0x9040, v0
	s_waitcnt vmcnt(6)
	ds_write2_b64 v1, v[36:37], v[38:39] offset1:1
	v_add_u32_e32 v1, 0xa080, v0
	s_waitcnt vmcnt(5)
	ds_write2_b64 v1, v[40:41], v[42:43] offset1:1
	v_add_u32_e32 v1, 0xb0c0, v0
	s_waitcnt vmcnt(4)
	ds_write2_b64 v1, v[44:45], v[46:47] offset1:1
	v_add_u32_e32 v1, 0xc100, v0
	v_ashrrev_i32_e32 v7, 31, v6
	s_waitcnt vmcnt(3)
	ds_write2_b64 v1, v[48:49], v[50:51] offset1:1
	v_add_u32_e32 v1, 0xd140, v0
	s_waitcnt vmcnt(2)
	ds_write2_b64 v1, v[52:53], v[54:55] offset1:1
	v_add_u32_e32 v1, 0xe180, v0
	v_add_u32_e32 v0, 0xf1c0, v0
	v_ashrrev_i32_e32 v9, 31, v8
	s_waitcnt vmcnt(1)
	ds_write2_b64 v1, v[56:57], v[58:59] offset1:1
	v_ashrrev_i32_e32 v11, 31, v10
	v_lshl_add_u64 v[2:3], v[2:3], 1, s[4:5]
	s_waitcnt vmcnt(0)
	ds_write2_b64 v0, v[60:61], v[62:63] offset1:1
	v_min_i32_e32 v0, v13, v12
	v_ashrrev_i32_e32 v1, 31, v0
	v_lshl_add_u64 v[0:1], v[0:1], 1, s[4:5]
	s_waitcnt lgkmcnt(0)
	s_barrier
	global_load_ushort v100, v[0:1], off
	v_add_u32_e32 v0, s14, v107
	v_min_i32_e32 v0, v0, v12
	v_add_u32_e32 v13, 0x380, v13
	v_ashrrev_i32_e32 v1, 31, v0
	v_min_i32_e32 v12, v13, v12
	v_lshl_add_u64 v[0:1], v[0:1], 1, s[4:5]
	v_ashrrev_i32_e32 v13, 31, v12
	v_lshl_add_u64 v[4:5], v[4:5], 1, s[4:5]
	v_lshl_add_u64 v[6:7], v[6:7], 1, s[4:5]
	v_lshl_add_u64 v[8:9], v[8:9], 1, s[4:5]
	v_lshl_add_u64 v[10:11], v[10:11], 1, s[4:5]
	v_lshl_add_u64 v[12:13], v[12:13], 1, s[4:5]
	global_load_ushort v117, v[0:1], off
	global_load_ushort v116, v[2:3], off
	global_load_ushort v115, v[4:5], off
	global_load_ushort v114, v[6:7], off
	global_load_ushort v113, v[8:9], off
	global_load_ushort v112, v[10:11], off
	global_load_ushort v111, v[12:13], off
	v_mov_b32_e32 v1, s39
	s_waitcnt vmcnt(7)
	v_and_b32_e32 v118, 0x1fff, v100
	v_or_b32_e32 v0, s38, v118
	v_lshlrev_b64 v[0:1], 7, v[0:1]
	v_lshl_add_u64 v[0:1], v[102:103], 0, v[0:1]
	global_load_dwordx4 v[80:83], v[0:1], off offset:96
	global_load_dwordx4 v[84:87], v[0:1], off offset:64
	global_load_dwordx4 v[88:91], v[0:1], off offset:32
	global_load_dwordx4 v[92:95], v[0:1], off
	s_waitcnt vmcnt(3)
	v_mov_b64_e32 v[64:65], v[80:81]
	s_waitcnt vmcnt(2)
	v_mov_b64_e32 v[68:69], v[84:85]
	s_waitcnt vmcnt(1)
	v_mov_b64_e32 v[72:73], v[88:89]
	s_waitcnt vmcnt(0)
	v_mov_b64_e32 v[76:77], v[92:93]
	v_mov_b64_e32 v[66:67], v[82:83]
	v_mov_b64_e32 v[70:71], v[86:87]
	v_mov_b64_e32 v[74:75], v[90:91]
	v_mov_b64_e32 v[78:79], v[94:95]
	s_cbranch_vccnz .LBB0_1251
	v_and_b32_e32 v0, 0x1fff, v117
	v_or_b32_e32 v0, s38, v0
	v_mov_b32_e32 v1, s39
	v_lshlrev_b64 v[0:1], 7, v[0:1]
	v_lshl_add_u64 v[0:1], v[102:103], 0, v[0:1]
	global_load_dwordx4 v[76:79], v[0:1], off
	global_load_dwordx4 v[72:75], v[0:1], off offset:32
	global_load_dwordx4 v[68:71], v[0:1], off offset:64
	global_load_dwordx4 v[64:67], v[0:1], off offset:96
